# w_in projection epilogue: per-row sum-of-squares loads of rows 1-3 / 5-7 issued with row 0 / 4, their vmcnt(0) drains (which also waited for the previous rows' stores) removed
# baseline (speedup 1.0000x reference)
.LBB0_653:
	s_lshl_b32 s35, s13, 8
	s_add_i32 s35, s35, s28
	v_or_b32_e32 v142, s35, v137
	v_ashrrev_i32_e32 v143, 31, v142
	v_lshl_add_u64 v[162:163], v[142:143], 2, s[8:9]
	global_load_dword v148, v[162:163], off
	global_load_dword v207, v[162:163], off offset:64
	global_load_dword v208, v[162:163], off offset:128
	global_load_dword v209, v[162:163], off offset:192
	s_lshl_b32 s0, s12, 8
	s_ashr_i32 s58, s12, 2
	s_and_b32 s20, s0, 0x300
	s_cmp_gt_i32 s58, 2
	s_cselect_b64 s[2:3], -1, 0
	s_add_i32 s60, s0, 0xffffe000
	s_movk_i32 s0, 0x3000
	v_mad_i64_i32 v[168:169], s[0:1], v142, s0, 0
	s_ashr_i32 s61, s60, 31
	v_lshlrev_b64 v[166:167], 10, v[142:143]
	s_mov_b64 s[0:1], -1
	s_waitcnt vmcnt(0)
	v_fmamk_f32 v148, v148, 0x3a000000, v193
	v_cmp_gt_f32_e32 vcc, s77, v148
	v_mul_f32_e32 v164, 0x4b800000, v148
	s_nop 0
	v_cndmask_b32_e32 v148, v148, v164, vcc
	v_rsq_f32_e32 v148, v148
	s_nop 0
	v_mul_f32_e32 v164, 0x45800000, v148
	v_cndmask_b32_e32 v170, v148, v164, vcc
	v_lshlrev_b64 v[164:165], 11, v[142:143]
	v_pk_mul_f32 v[174:175], v[126:127], v[170:171] op_sel_hi:[1,0]
	v_pk_mul_f32 v[178:179], v[124:125], v[170:171] op_sel_hi:[1,0]
	v_pk_mul_f32 v[172:173], v[122:123], v[170:171] op_sel_hi:[1,0]
	v_pk_mul_f32 v[176:177], v[120:121], v[170:171] op_sel_hi:[1,0]
	v_or_b32_e32 v143, s20, v136
	s_and_b64 vcc, exec, s[2:3]
	s_cbranch_vccz .LBB0_674
	s_cmp_lt_i32 s58, 5
	s_cbranch_scc1 .LBB0_668
	s_cmp_lt_i32 s58, 6
	s_cbranch_scc1 .LBB0_665
	s_cmp_lt_i32 s58, 7
	s_cbranch_scc1 .LBB0_662
	s_cmp_lg_u32 s58, 7
	s_cbranch_scc0 .LBB0_659
	v_mul_f32_e32 v121, 0xbfb8aa3b, v176
	v_exp_f32_e32 v121, v121
	v_mul_f32_e32 v122, 0xbfb8aa3b, v179
	v_mul_f32_e32 v123, 0xbfb8aa3b, v177
	v_exp_f32_e32 v122, v122
	v_exp_f32_e32 v123, v123
	v_add_f32_e32 v121, 1.0, v121
	v_mul_f32_e32 v120, 0xbfb8aa3b, v178
	v_rcp_f32_e32 v124, v121
	v_add_f32_e32 v121, 1.0, v122
	v_add_f32_e32 v122, 1.0, v123
	v_mul_f32_e32 v123, 0xbfb8aa3b, v174
	v_mul_f32_e32 v125, 0xbfb8aa3b, v172
	v_mul_f32_e32 v126, 0xbfb8aa3b, v175
	v_mul_f32_e32 v127, 0xbfb8aa3b, v173
	v_exp_f32_e32 v120, v120
	v_exp_f32_e32 v123, v123
	v_exp_f32_e32 v125, v125
	v_exp_f32_e32 v126, v126
	v_exp_f32_e32 v127, v127
	v_add_f32_e32 v120, 1.0, v120
	v_add_f32_e32 v123, 1.0, v123
	v_add_f32_e32 v125, 1.0, v125
	v_add_f32_e32 v126, 1.0, v126
	v_add_f32_e32 v127, 1.0, v127
	v_rcp_f32_e32 v120, v120
	v_rcp_f32_e32 v121, v121
	v_rcp_f32_e32 v122, v122
	v_rcp_f32_e32 v123, v123
	v_rcp_f32_e32 v125, v125
	v_rcp_f32_e32 v126, v126
	v_rcp_f32_e32 v127, v127
	v_cvt_pk_bf16_f32 v120, v120, v121
	v_cvt_pk_bf16_f32 v122, v124, v122
	v_cvt_pk_bf16_f32 v121, v123, v126
	v_cvt_pk_bf16_f32 v123, v125, v127
	v_lshl_add_u64 v[124:125], s[36:37], 0, v[168:169]
	v_lshl_add_u64 v[124:125], s[60:61], 1, v[124:125]
	v_lshlrev_b32_e32 v148, 1, v136
	v_lshl_add_u64 v[124:125], v[124:125], 0, v[148:149]
	s_mov_b64 s[0:1], 0
	global_store_dwordx4 v[124:125], v[120:123], off

.LBB0_699:
	s_nop 1
	v_mov_b32_e32 v112, v207
	v_or_b32_e32 v116, 16, v142
	v_ashrrev_i32_e32 v117, 31, v116
	s_movk_i32 s0, 0x3000
	v_lshlrev_b64 v[114:115], 10, v[116:117]
	v_fmamk_f32 v112, v112, 0x3a000000, v193
	v_cmp_gt_f32_e32 vcc, s77, v112
	v_mul_f32_e32 v113, 0x4b800000, v112
	s_nop 0
	v_cndmask_b32_e32 v112, v112, v113, vcc
	v_rsq_f32_e32 v112, v112
	s_nop 0
	v_mul_f32_e32 v113, 0x45800000, v112
	v_cndmask_b32_e32 v118, v112, v113, vcc
	v_lshlrev_b64 v[112:113], 11, v[116:117]
	v_mad_i64_i32 v[116:117], s[0:1], v116, s0, 0
	v_pk_mul_f32 v[122:123], v[110:111], v[118:119] op_sel_hi:[1,0]
	v_pk_mul_f32 v[126:127], v[108:109], v[118:119] op_sel_hi:[1,0]
	v_pk_mul_f32 v[120:121], v[106:107], v[118:119] op_sel_hi:[1,0]
	v_pk_mul_f32 v[124:125], v[104:105], v[118:119] op_sel_hi:[1,0]
	s_mov_b64 s[0:1], -1
	s_and_b64 vcc, exec, s[44:45]
	s_cbranch_vccnz .LBB0_720
	s_cmp_lt_i32 s58, 5
	s_cbranch_scc1 .LBB0_714
	s_cmp_lt_i32 s58, 6
	s_cbranch_scc1 .LBB0_711
	s_cmp_lt_i32 s58, 7
	s_cbranch_scc1 .LBB0_708
	s_cmp_lg_u32 s58, 7
	s_cbranch_scc0 .LBB0_705
	v_mul_f32_e32 v105, 0xbfb8aa3b, v124
	v_exp_f32_e32 v105, v105
	v_mul_f32_e32 v106, 0xbfb8aa3b, v127
	v_mul_f32_e32 v107, 0xbfb8aa3b, v125
	v_exp_f32_e32 v106, v106
	v_exp_f32_e32 v107, v107
	v_add_f32_e32 v105, 1.0, v105
	v_mul_f32_e32 v104, 0xbfb8aa3b, v126
	v_rcp_f32_e32 v108, v105
	v_add_f32_e32 v105, 1.0, v106
	v_add_f32_e32 v106, 1.0, v107
	v_mul_f32_e32 v107, 0xbfb8aa3b, v122
	v_mul_f32_e32 v109, 0xbfb8aa3b, v120
	v_mul_f32_e32 v110, 0xbfb8aa3b, v123
	v_mul_f32_e32 v111, 0xbfb8aa3b, v121
	v_exp_f32_e32 v104, v104
	v_exp_f32_e32 v107, v107
	v_exp_f32_e32 v109, v109
	v_exp_f32_e32 v110, v110
	v_exp_f32_e32 v111, v111
	v_add_f32_e32 v104, 1.0, v104
	v_add_f32_e32 v107, 1.0, v107
	v_add_f32_e32 v109, 1.0, v109
	v_add_f32_e32 v110, 1.0, v110
	v_add_f32_e32 v111, 1.0, v111
	v_rcp_f32_e32 v104, v104
	v_rcp_f32_e32 v105, v105
	v_rcp_f32_e32 v106, v106
	v_rcp_f32_e32 v107, v107
	v_rcp_f32_e32 v109, v109
	v_rcp_f32_e32 v110, v110
	v_rcp_f32_e32 v111, v111
	v_cvt_pk_bf16_f32 v104, v104, v105
	v_cvt_pk_bf16_f32 v106, v108, v106
	v_cvt_pk_bf16_f32 v105, v107, v110
	v_cvt_pk_bf16_f32 v107, v109, v111
	v_lshl_add_u64 v[108:109], s[36:37], 0, v[116:117]
	v_lshl_add_u64 v[108:109], s[60:61], 1, v[108:109]
	v_lshl_add_u64 v[108:109], v[108:109], 0, v[148:149]
	global_store_dwordx4 v[108:109], v[104:107], off
	s_mov_b64 s[0:1], 0

.LBB0_745:
	s_nop 1
	v_mov_b32_e32 v96, v208
	v_or_b32_e32 v100, 32, v142
	v_ashrrev_i32_e32 v101, 31, v100
	s_movk_i32 s0, 0x3000
	v_lshlrev_b64 v[98:99], 10, v[100:101]
	v_fmamk_f32 v96, v96, 0x3a000000, v193
	v_cmp_gt_f32_e32 vcc, s77, v96
	v_mul_f32_e32 v97, 0x4b800000, v96
	s_nop 0
	v_cndmask_b32_e32 v96, v96, v97, vcc
	v_rsq_f32_e32 v96, v96
	s_nop 0
	v_mul_f32_e32 v97, 0x45800000, v96
	v_cndmask_b32_e32 v102, v96, v97, vcc
	v_lshlrev_b64 v[96:97], 11, v[100:101]
	v_mad_i64_i32 v[100:101], s[0:1], v100, s0, 0
	v_pk_mul_f32 v[106:107], v[94:95], v[102:103] op_sel_hi:[1,0]
	v_pk_mul_f32 v[110:111], v[92:93], v[102:103] op_sel_hi:[1,0]
	v_pk_mul_f32 v[104:105], v[90:91], v[102:103] op_sel_hi:[1,0]
	v_pk_mul_f32 v[108:109], v[88:89], v[102:103] op_sel_hi:[1,0]
	s_mov_b64 s[0:1], -1
	s_and_b64 vcc, exec, s[44:45]
	s_cbranch_vccnz .LBB0_766
	s_cmp_lt_i32 s58, 5
	s_cbranch_scc1 .LBB0_760
	s_cmp_lt_i32 s58, 6
	s_cbranch_scc1 .LBB0_757
	s_cmp_lt_i32 s58, 7
	s_cbranch_scc1 .LBB0_754
	s_cmp_lg_u32 s58, 7
	s_cbranch_scc0 .LBB0_751
	v_mul_f32_e32 v89, 0xbfb8aa3b, v108
	v_exp_f32_e32 v89, v89
	v_mul_f32_e32 v90, 0xbfb8aa3b, v111
	v_mul_f32_e32 v91, 0xbfb8aa3b, v109
	v_exp_f32_e32 v90, v90
	v_exp_f32_e32 v91, v91
	v_add_f32_e32 v89, 1.0, v89
	v_mul_f32_e32 v88, 0xbfb8aa3b, v110
	v_rcp_f32_e32 v92, v89
	v_add_f32_e32 v89, 1.0, v90
	v_add_f32_e32 v90, 1.0, v91
	v_mul_f32_e32 v91, 0xbfb8aa3b, v106
	v_mul_f32_e32 v93, 0xbfb8aa3b, v104
	v_mul_f32_e32 v94, 0xbfb8aa3b, v107
	v_mul_f32_e32 v95, 0xbfb8aa3b, v105
	v_exp_f32_e32 v88, v88
	v_exp_f32_e32 v91, v91
	v_exp_f32_e32 v93, v93
	v_exp_f32_e32 v94, v94
	v_exp_f32_e32 v95, v95
	v_add_f32_e32 v88, 1.0, v88
	v_add_f32_e32 v91, 1.0, v91
	v_add_f32_e32 v93, 1.0, v93
	v_add_f32_e32 v94, 1.0, v94
	v_add_f32_e32 v95, 1.0, v95
	v_rcp_f32_e32 v88, v88
	v_rcp_f32_e32 v89, v89
	v_rcp_f32_e32 v90, v90
	v_rcp_f32_e32 v91, v91
	v_rcp_f32_e32 v93, v93
	v_rcp_f32_e32 v94, v94
	v_rcp_f32_e32 v95, v95
	v_cvt_pk_bf16_f32 v88, v88, v89
	v_cvt_pk_bf16_f32 v90, v92, v90
	v_cvt_pk_bf16_f32 v89, v91, v94
	v_cvt_pk_bf16_f32 v91, v93, v95
	v_lshl_add_u64 v[92:93], s[36:37], 0, v[100:101]
	v_lshl_add_u64 v[92:93], s[60:61], 1, v[92:93]
	v_lshl_add_u64 v[92:93], v[92:93], 0, v[148:149]
	global_store_dwordx4 v[92:93], v[88:91], off
	s_mov_b64 s[0:1], 0

.LBB0_791:
	s_nop 1
	v_mov_b32_e32 v80, v209
	v_or_b32_e32 v84, 48, v142
	v_ashrrev_i32_e32 v85, 31, v84
	s_movk_i32 s0, 0x3000
	v_lshlrev_b64 v[82:83], 10, v[84:85]
	v_fmamk_f32 v80, v80, 0x3a000000, v193
	v_cmp_gt_f32_e32 vcc, s77, v80
	v_mul_f32_e32 v81, 0x4b800000, v80
	s_nop 0
	v_cndmask_b32_e32 v80, v80, v81, vcc
	v_rsq_f32_e32 v80, v80
	s_nop 0
	v_mul_f32_e32 v81, 0x45800000, v80
	v_cndmask_b32_e32 v86, v80, v81, vcc
	v_lshlrev_b64 v[80:81], 11, v[84:85]
	v_mad_i64_i32 v[84:85], s[0:1], v84, s0, 0
	v_pk_mul_f32 v[90:91], v[78:79], v[86:87] op_sel_hi:[1,0]
	v_pk_mul_f32 v[94:95], v[76:77], v[86:87] op_sel_hi:[1,0]
	v_pk_mul_f32 v[88:89], v[74:75], v[86:87] op_sel_hi:[1,0]
	v_pk_mul_f32 v[92:93], v[72:73], v[86:87] op_sel_hi:[1,0]
	s_mov_b64 s[0:1], -1
	s_and_b64 vcc, exec, s[44:45]
	s_cbranch_vccnz .LBB0_812
	s_cmp_lt_i32 s58, 5
	s_cbranch_scc1 .LBB0_806
	s_cmp_lt_i32 s58, 6
	s_cbranch_scc1 .LBB0_803
	s_cmp_lt_i32 s58, 7
	s_cbranch_scc1 .LBB0_800
	s_cmp_lg_u32 s58, 7
	s_cbranch_scc0 .LBB0_797
	v_mul_f32_e32 v73, 0xbfb8aa3b, v92
	v_exp_f32_e32 v73, v73
	v_mul_f32_e32 v74, 0xbfb8aa3b, v95
	v_mul_f32_e32 v75, 0xbfb8aa3b, v93
	v_exp_f32_e32 v74, v74
	v_exp_f32_e32 v75, v75
	v_add_f32_e32 v73, 1.0, v73
	v_mul_f32_e32 v72, 0xbfb8aa3b, v94
	v_rcp_f32_e32 v76, v73
	v_add_f32_e32 v73, 1.0, v74
	v_add_f32_e32 v74, 1.0, v75
	v_mul_f32_e32 v75, 0xbfb8aa3b, v90
	v_mul_f32_e32 v77, 0xbfb8aa3b, v88
	v_mul_f32_e32 v78, 0xbfb8aa3b, v91
	v_mul_f32_e32 v79, 0xbfb8aa3b, v89
	v_exp_f32_e32 v72, v72
	v_exp_f32_e32 v75, v75
	v_exp_f32_e32 v77, v77
	v_exp_f32_e32 v78, v78
	v_exp_f32_e32 v79, v79
	v_add_f32_e32 v72, 1.0, v72
	v_add_f32_e32 v75, 1.0, v75
	v_add_f32_e32 v77, 1.0, v77
	v_add_f32_e32 v78, 1.0, v78
	v_add_f32_e32 v79, 1.0, v79
	v_rcp_f32_e32 v72, v72
	v_rcp_f32_e32 v73, v73
	v_rcp_f32_e32 v74, v74
	v_rcp_f32_e32 v75, v75
	v_rcp_f32_e32 v77, v77
	v_rcp_f32_e32 v78, v78
	v_rcp_f32_e32 v79, v79
	v_cvt_pk_bf16_f32 v72, v72, v73
	v_cvt_pk_bf16_f32 v74, v76, v74
	v_cvt_pk_bf16_f32 v73, v75, v78
	v_cvt_pk_bf16_f32 v75, v77, v79
	v_lshl_add_u64 v[76:77], s[36:37], 0, v[84:85]
	v_lshl_add_u64 v[76:77], s[60:61], 1, v[76:77]
	v_lshl_add_u64 v[76:77], v[76:77], 0, v[148:149]
	global_store_dwordx4 v[76:77], v[72:75], off
	s_mov_b64 s[0:1], 0

.LBB0_837:
	s_addk_i32 s35, 0x80
	s_nop 0
	v_or_b32_e32 v64, s35, v137
	v_ashrrev_i32_e32 v65, 31, v64
	v_lshl_add_u64 v[66:67], v[64:65], 2, s[8:9]
	global_load_dword v68, v[66:67], off
	global_load_dword v210, v[66:67], off offset:64
	global_load_dword v211, v[66:67], off offset:128
	global_load_dword v212, v[66:67], off offset:192
	s_movk_i32 s0, 0x3000
	v_mad_i64_i32 v[72:73], s[0:1], v64, s0, 0
	v_lshlrev_b64 v[70:71], 10, v[64:65]
	s_mov_b64 s[0:1], -1
	s_waitcnt vmcnt(0)
	v_fmamk_f32 v68, v68, 0x3a000000, v193
	v_cmp_gt_f32_e32 vcc, s77, v68
	v_mul_f32_e32 v69, 0x4b800000, v68
	s_nop 0
	v_cndmask_b32_e32 v68, v68, v69, vcc
	v_rsq_f32_e32 v68, v68
	s_nop 0
	v_mul_f32_e32 v69, 0x45800000, v68
	v_cndmask_b32_e32 v74, v68, v69, vcc
	v_lshlrev_b64 v[68:69], 11, v[64:65]
	v_pk_mul_f32 v[78:79], v[62:63], v[74:75] op_sel_hi:[1,0]
	v_pk_mul_f32 v[82:83], v[60:61], v[74:75] op_sel_hi:[1,0]
	v_pk_mul_f32 v[76:77], v[58:59], v[74:75] op_sel_hi:[1,0]
	v_pk_mul_f32 v[80:81], v[56:57], v[74:75] op_sel_hi:[1,0]
	s_and_b64 vcc, exec, s[44:45]
	s_cbranch_vccnz .LBB0_858
	s_cmp_lt_i32 s58, 5
	s_cbranch_scc1 .LBB0_852
	s_cmp_lt_i32 s58, 6
	s_cbranch_scc1 .LBB0_849
	s_cmp_lt_i32 s58, 7
	s_cbranch_scc1 .LBB0_846
	s_cmp_lg_u32 s58, 7
	s_cbranch_scc0 .LBB0_843
	v_mul_f32_e32 v57, 0xbfb8aa3b, v80
	v_exp_f32_e32 v57, v57
	v_mul_f32_e32 v58, 0xbfb8aa3b, v83
	v_mul_f32_e32 v59, 0xbfb8aa3b, v81
	v_exp_f32_e32 v58, v58
	v_exp_f32_e32 v59, v59
	v_add_f32_e32 v57, 1.0, v57
	v_mul_f32_e32 v56, 0xbfb8aa3b, v82
	v_rcp_f32_e32 v60, v57
	v_add_f32_e32 v57, 1.0, v58
	v_add_f32_e32 v58, 1.0, v59
	v_mul_f32_e32 v59, 0xbfb8aa3b, v78
	v_mul_f32_e32 v61, 0xbfb8aa3b, v76
	v_mul_f32_e32 v62, 0xbfb8aa3b, v79
	v_mul_f32_e32 v63, 0xbfb8aa3b, v77
	v_exp_f32_e32 v56, v56
	v_exp_f32_e32 v59, v59
	v_exp_f32_e32 v61, v61
	v_exp_f32_e32 v62, v62
	v_exp_f32_e32 v63, v63
	v_add_f32_e32 v56, 1.0, v56
	v_add_f32_e32 v59, 1.0, v59
	v_add_f32_e32 v61, 1.0, v61
	v_add_f32_e32 v62, 1.0, v62
	v_add_f32_e32 v63, 1.0, v63
	v_rcp_f32_e32 v56, v56
	v_rcp_f32_e32 v57, v57
	v_rcp_f32_e32 v58, v58
	v_rcp_f32_e32 v59, v59
	v_rcp_f32_e32 v61, v61
	v_rcp_f32_e32 v62, v62
	v_rcp_f32_e32 v63, v63
	v_cvt_pk_bf16_f32 v56, v56, v57
	v_cvt_pk_bf16_f32 v58, v60, v58
	v_cvt_pk_bf16_f32 v57, v59, v62
	v_cvt_pk_bf16_f32 v59, v61, v63
	v_lshl_add_u64 v[60:61], s[36:37], 0, v[72:73]
	v_lshl_add_u64 v[60:61], s[60:61], 1, v[60:61]
	v_lshl_add_u64 v[60:61], v[60:61], 0, v[148:149]
	global_store_dwordx4 v[60:61], v[56:59], off
	s_mov_b64 s[0:1], 0

.LBB0_883:
	s_nop 1
	v_mov_b32_e32 v48, v210
	v_or_b32_e32 v52, 16, v64
	v_ashrrev_i32_e32 v53, 31, v52
	s_movk_i32 s0, 0x3000
	v_lshlrev_b64 v[50:51], 10, v[52:53]
	v_fmamk_f32 v48, v48, 0x3a000000, v193
	v_cmp_gt_f32_e32 vcc, s77, v48
	v_mul_f32_e32 v49, 0x4b800000, v48
	s_nop 0
	v_cndmask_b32_e32 v48, v48, v49, vcc
	v_rsq_f32_e32 v48, v48
	s_nop 0
	v_mul_f32_e32 v49, 0x45800000, v48
	v_cndmask_b32_e32 v54, v48, v49, vcc
	v_lshlrev_b64 v[48:49], 11, v[52:53]
	v_mad_i64_i32 v[52:53], s[0:1], v52, s0, 0
	v_pk_mul_f32 v[58:59], v[46:47], v[54:55] op_sel_hi:[1,0]
	v_pk_mul_f32 v[62:63], v[44:45], v[54:55] op_sel_hi:[1,0]
	v_pk_mul_f32 v[56:57], v[42:43], v[54:55] op_sel_hi:[1,0]
	v_pk_mul_f32 v[60:61], v[40:41], v[54:55] op_sel_hi:[1,0]
	s_mov_b64 s[0:1], -1
	s_and_b64 vcc, exec, s[44:45]
	s_cbranch_vccnz .LBB0_904
	s_cmp_lt_i32 s58, 5
	s_cbranch_scc1 .LBB0_898
	s_cmp_lt_i32 s58, 6
	s_cbranch_scc1 .LBB0_895
	s_cmp_lt_i32 s58, 7
	s_cbranch_scc1 .LBB0_892
	s_cmp_lg_u32 s58, 7
	s_cbranch_scc0 .LBB0_889
	v_mul_f32_e32 v41, 0xbfb8aa3b, v60
	v_exp_f32_e32 v41, v41
	v_mul_f32_e32 v42, 0xbfb8aa3b, v63
	v_mul_f32_e32 v43, 0xbfb8aa3b, v61
	v_exp_f32_e32 v42, v42
	v_exp_f32_e32 v43, v43
	v_add_f32_e32 v41, 1.0, v41
	v_mul_f32_e32 v40, 0xbfb8aa3b, v62
	v_rcp_f32_e32 v44, v41
	v_add_f32_e32 v41, 1.0, v42
	v_add_f32_e32 v42, 1.0, v43
	v_mul_f32_e32 v43, 0xbfb8aa3b, v58
	v_mul_f32_e32 v45, 0xbfb8aa3b, v56
	v_mul_f32_e32 v46, 0xbfb8aa3b, v59
	v_mul_f32_e32 v47, 0xbfb8aa3b, v57
	v_exp_f32_e32 v40, v40
	v_exp_f32_e32 v43, v43
	v_exp_f32_e32 v45, v45
	v_exp_f32_e32 v46, v46
	v_exp_f32_e32 v47, v47
	v_add_f32_e32 v40, 1.0, v40
	v_add_f32_e32 v43, 1.0, v43
	v_add_f32_e32 v45, 1.0, v45
	v_add_f32_e32 v46, 1.0, v46
	v_add_f32_e32 v47, 1.0, v47
	v_rcp_f32_e32 v40, v40
	v_rcp_f32_e32 v41, v41
	v_rcp_f32_e32 v42, v42
	v_rcp_f32_e32 v43, v43
	v_rcp_f32_e32 v45, v45
	v_rcp_f32_e32 v46, v46
	v_rcp_f32_e32 v47, v47
	v_cvt_pk_bf16_f32 v40, v40, v41
	v_cvt_pk_bf16_f32 v42, v44, v42
	v_cvt_pk_bf16_f32 v41, v43, v46
	v_cvt_pk_bf16_f32 v43, v45, v47
	v_lshl_add_u64 v[44:45], s[36:37], 0, v[52:53]
	v_lshl_add_u64 v[44:45], s[60:61], 1, v[44:45]
	v_lshl_add_u64 v[44:45], v[44:45], 0, v[148:149]
	global_store_dwordx4 v[44:45], v[40:43], off
	s_mov_b64 s[0:1], 0

.LBB0_929:
	s_nop 1
	v_mov_b32_e32 v32, v211
	v_or_b32_e32 v36, 32, v64
	v_ashrrev_i32_e32 v37, 31, v36
	s_movk_i32 s0, 0x3000
	v_lshlrev_b64 v[34:35], 10, v[36:37]
	v_fmamk_f32 v32, v32, 0x3a000000, v193
	v_cmp_gt_f32_e32 vcc, s77, v32
	v_mul_f32_e32 v33, 0x4b800000, v32
	s_nop 0
	v_cndmask_b32_e32 v32, v32, v33, vcc
	v_rsq_f32_e32 v32, v32
	s_nop 0
	v_mul_f32_e32 v33, 0x45800000, v32
	v_cndmask_b32_e32 v38, v32, v33, vcc
	v_lshlrev_b64 v[32:33], 11, v[36:37]
	v_mad_i64_i32 v[36:37], s[0:1], v36, s0, 0
	v_pk_mul_f32 v[42:43], v[30:31], v[38:39] op_sel_hi:[1,0]
	v_pk_mul_f32 v[46:47], v[28:29], v[38:39] op_sel_hi:[1,0]
	v_pk_mul_f32 v[40:41], v[26:27], v[38:39] op_sel_hi:[1,0]
	v_pk_mul_f32 v[44:45], v[24:25], v[38:39] op_sel_hi:[1,0]
	s_mov_b64 s[0:1], -1
	s_and_b64 vcc, exec, s[44:45]
	s_cbranch_vccnz .LBB0_950
	s_cmp_lt_i32 s58, 5
	s_cbranch_scc1 .LBB0_944
	s_cmp_lt_i32 s58, 6
	s_cbranch_scc1 .LBB0_941
	s_cmp_lt_i32 s58, 7
	s_cbranch_scc1 .LBB0_938
	s_cmp_lg_u32 s58, 7
	s_cbranch_scc0 .LBB0_935
	v_mul_f32_e32 v25, 0xbfb8aa3b, v44
	v_exp_f32_e32 v25, v25
	v_mul_f32_e32 v26, 0xbfb8aa3b, v47
	v_mul_f32_e32 v27, 0xbfb8aa3b, v45
	v_exp_f32_e32 v26, v26
	v_exp_f32_e32 v27, v27
	v_add_f32_e32 v25, 1.0, v25
	v_mul_f32_e32 v24, 0xbfb8aa3b, v46
	v_rcp_f32_e32 v28, v25
	v_add_f32_e32 v25, 1.0, v26
	v_add_f32_e32 v26, 1.0, v27
	v_mul_f32_e32 v27, 0xbfb8aa3b, v42
	v_mul_f32_e32 v29, 0xbfb8aa3b, v40
	v_mul_f32_e32 v30, 0xbfb8aa3b, v43
	v_mul_f32_e32 v31, 0xbfb8aa3b, v41
	v_exp_f32_e32 v24, v24
	v_exp_f32_e32 v27, v27
	v_exp_f32_e32 v29, v29
	v_exp_f32_e32 v30, v30
	v_exp_f32_e32 v31, v31
	v_add_f32_e32 v24, 1.0, v24
	v_add_f32_e32 v27, 1.0, v27
	v_add_f32_e32 v29, 1.0, v29
	v_add_f32_e32 v30, 1.0, v30
	v_add_f32_e32 v31, 1.0, v31
	v_rcp_f32_e32 v24, v24
	v_rcp_f32_e32 v25, v25
	v_rcp_f32_e32 v26, v26
	v_rcp_f32_e32 v27, v27
	v_rcp_f32_e32 v29, v29
	v_rcp_f32_e32 v30, v30
	v_rcp_f32_e32 v31, v31
	v_cvt_pk_bf16_f32 v24, v24, v25
	v_cvt_pk_bf16_f32 v26, v28, v26
	v_cvt_pk_bf16_f32 v25, v27, v30
	v_cvt_pk_bf16_f32 v27, v29, v31
	v_lshl_add_u64 v[28:29], s[36:37], 0, v[36:37]
	v_lshl_add_u64 v[28:29], s[60:61], 1, v[28:29]
	v_lshl_add_u64 v[28:29], v[28:29], 0, v[148:149]
	global_store_dwordx4 v[28:29], v[24:27], off
	s_mov_b64 s[0:1], 0

.LBB0_975:
	s_nop 1
	v_mov_b32_e32 v16, v212
	v_or_b32_e32 v20, 48, v64
	v_ashrrev_i32_e32 v21, 31, v20
	s_movk_i32 s0, 0x3000
	v_lshlrev_b64 v[18:19], 10, v[20:21]
	v_fmamk_f32 v16, v16, 0x3a000000, v193
	v_cmp_gt_f32_e32 vcc, s77, v16
	v_mul_f32_e32 v17, 0x4b800000, v16
	s_nop 0
	v_cndmask_b32_e32 v16, v16, v17, vcc
	v_rsq_f32_e32 v16, v16
	s_nop 0
	v_mul_f32_e32 v17, 0x45800000, v16
	v_cndmask_b32_e32 v22, v16, v17, vcc
	v_lshlrev_b64 v[16:17], 11, v[20:21]
	v_mad_i64_i32 v[20:21], s[0:1], v20, s0, 0
	v_pk_mul_f32 v[26:27], v[14:15], v[22:23] op_sel_hi:[1,0]
	v_pk_mul_f32 v[30:31], v[12:13], v[22:23] op_sel_hi:[1,0]
	v_pk_mul_f32 v[24:25], v[10:11], v[22:23] op_sel_hi:[1,0]
	v_pk_mul_f32 v[28:29], v[8:9], v[22:23] op_sel_hi:[1,0]
	s_mov_b64 s[0:1], -1
	s_and_b64 vcc, exec, s[44:45]
	s_cbranch_vccnz .LBB0_996
	s_cmp_lt_i32 s58, 5
	s_cbranch_scc1 .LBB0_990
	s_cmp_lt_i32 s58, 6
	s_cbranch_scc1 .LBB0_987
	s_cmp_lt_i32 s58, 7
	s_cbranch_scc1 .LBB0_984
	s_cmp_lg_u32 s58, 7
	s_cbranch_scc0 .LBB0_981
	v_mul_f32_e32 v9, 0xbfb8aa3b, v28
	v_exp_f32_e32 v9, v9
	v_mul_f32_e32 v10, 0xbfb8aa3b, v31
	v_mul_f32_e32 v11, 0xbfb8aa3b, v29
	v_exp_f32_e32 v10, v10
	v_exp_f32_e32 v11, v11
	v_add_f32_e32 v9, 1.0, v9
	v_mul_f32_e32 v8, 0xbfb8aa3b, v30
	v_rcp_f32_e32 v12, v9
	v_add_f32_e32 v9, 1.0, v10
	v_add_f32_e32 v10, 1.0, v11
	v_mul_f32_e32 v11, 0xbfb8aa3b, v26
	v_mul_f32_e32 v13, 0xbfb8aa3b, v24
	v_mul_f32_e32 v14, 0xbfb8aa3b, v27
	v_mul_f32_e32 v15, 0xbfb8aa3b, v25
	v_exp_f32_e32 v8, v8
	v_exp_f32_e32 v11, v11
	v_exp_f32_e32 v13, v13
	v_exp_f32_e32 v14, v14
	v_exp_f32_e32 v15, v15
	v_add_f32_e32 v8, 1.0, v8
	v_add_f32_e32 v11, 1.0, v11
	v_add_f32_e32 v13, 1.0, v13
	v_add_f32_e32 v14, 1.0, v14
	v_add_f32_e32 v15, 1.0, v15
	v_rcp_f32_e32 v8, v8
	v_rcp_f32_e32 v9, v9
	v_rcp_f32_e32 v10, v10
	v_rcp_f32_e32 v11, v11
	v_rcp_f32_e32 v13, v13
	v_rcp_f32_e32 v14, v14
	v_rcp_f32_e32 v15, v15
	v_cvt_pk_bf16_f32 v8, v8, v9
	v_cvt_pk_bf16_f32 v10, v12, v10
	v_cvt_pk_bf16_f32 v9, v11, v14
	v_cvt_pk_bf16_f32 v11, v13, v15
	v_lshl_add_u64 v[12:13], s[36:37], 0, v[20:21]
	v_lshl_add_u64 v[12:13], s[60:61], 1, v[12:13]
	v_lshl_add_u64 v[12:13], v[12:13], 0, v[148:149]
	global_store_dwordx4 v[12:13], v[8:11], off
	s_mov_b64 s[0:1], 0
